# as the FINAL-batched version but hipcc's vmcnt(0) drain before each tile's K-loop is kept: all epilogue stores complete before the accumulators are rewritten
# speedup vs baseline: 1.0083x; 1.0068x over previous
; DI void final_phase(KP p) {
;     ...
;   for (int row = blockIdx.x * 8 + wid; row < T; row += gridDim.x * 8) {
;     const float rs = row_rstd(P4, 4, 1.f / 1024.f, row);
; #pragma unroll
;     for (int q = 0; q < 4; ++q) {
;       const u32x2 xw = *(const u32x2*)(XR + (size_t)row * DM + 256 * q + 4 * lane);
;       f32x4 v; v[0] = __uint_as_float(xw.x << 16); v[1] = __uint_as_float(xw.x & 0xffff0000u); v[2] = __uint_as_float(xw.y << 16); v[3] = __uint_as_float(xw.y & 0xffff0000u);
;       const f32x4 g = *(const f32x4*)(fg + 256 * q + 4 * lane);
;       *(f32x4*)(p->out + (size_t)row * DM + 256 * q + 4 * lane) = v * rs * g;
;     }
.LBB0_18:
	v_ashrrev_i32_e32 v3, 31, v2
	v_lshl_add_u64 v[10:11], v[2:3], 2, s[16:17]
	v_add_co_u32_e32 v14, vcc, 0x20000, v10
	global_load_dword v12, v[10:11], off
	s_nop 0
	v_addc_co_u32_e32 v15, vcc, 0, v11, vcc
	v_add_co_u32_e32 v16, vcc, 0x40000, v10
	global_load_dword v14, v[14:15], off
	s_nop 0
	v_addc_co_u32_e32 v17, vcc, 0, v11, vcc
	v_add_co_u32_e32 v10, vcc, 0x60000, v10
	global_load_dword v13, v[16:17], off
	s_nop 0
	v_addc_co_u32_e32 v11, vcc, 0, v11, vcc
	global_load_dword v15, v[10:11], off
	v_lshlrev_b64 v[18:19], 11, v[2:3]
	v_lshl_add_u64 v[18:19], v[4:5], 0, v[18:19]
	global_load_dwordx2 v[184:185], v[18:19], off
	global_load_dwordx2 v[186:187], v[18:19], off offset:512
	global_load_dwordx2 v[188:189], v[18:19], off offset:1024
	global_load_dwordx2 v[190:191], v[18:19], off offset:1536
	v_lshlrev_b64 v[20:21], 12, v[2:3]
	v_lshl_add_u64 v[20:21], v[8:9], 0, v[20:21]
	v_add_u32_e32 v2, s96, v2
	v_cmp_lt_i32_e32 vcc, s89, v2
	s_or_b64 s[14:15], vcc, s[14:15]
	s_waitcnt vmcnt(0)
	v_pk_add_f32 v[10:11], v[12:13], v[14:15]
	s_nop 0
	v_add_f32_e32 v0, v10, v11
	v_fmamk_f32 v0, v0, 0x3a800000, v195
	v_cmp_gt_f32_e32 vcc, s57, v0
	v_mul_f32_e32 v10, 0x4b800000, v0
	s_nop 0
	v_cndmask_b32_e32 v0, v0, v10, vcc
	v_rsq_f32_e32 v0, v0
	s_nop 0
	v_mul_f32_e32 v10, 0x45800000, v0
	v_cndmask_b32_e32 v0, v0, v10, vcc
	v_lshlrev_b32_e32 v166, 16, v184
	v_and_b32_e32 v167, 0xffff0000, v184
	v_lshlrev_b32_e32 v168, 16, v185
	v_and_b32_e32 v169, 0xffff0000, v185
	v_pk_mul_f32 v[166:167], v[0:1], v[166:167] op_sel_hi:[0,1]
	v_pk_mul_f32 v[168:169], v[0:1], v[168:169] op_sel_hi:[0,1]
	v_pk_mul_f32 v[168:169], v[224:225], v[168:169]
	v_pk_mul_f32 v[166:167], v[222:223], v[166:167]
	global_store_dwordx4 v[20:21], v[166:169], off
	v_lshlrev_b32_e32 v170, 16, v186
	v_and_b32_e32 v171, 0xffff0000, v186
	v_lshlrev_b32_e32 v172, 16, v187
	v_and_b32_e32 v173, 0xffff0000, v187
	v_pk_mul_f32 v[170:171], v[0:1], v[170:171] op_sel_hi:[0,1]
	v_pk_mul_f32 v[172:173], v[0:1], v[172:173] op_sel_hi:[0,1]
	v_pk_mul_f32 v[172:173], v[228:229], v[172:173]
	v_pk_mul_f32 v[170:171], v[226:227], v[170:171]
	global_store_dwordx4 v[20:21], v[170:173], off offset:1024
	v_lshlrev_b32_e32 v216, 16, v188
	v_and_b32_e32 v217, 0xffff0000, v188
	v_lshlrev_b32_e32 v218, 16, v189
	v_and_b32_e32 v219, 0xffff0000, v189
	v_pk_mul_f32 v[216:217], v[0:1], v[216:217] op_sel_hi:[0,1]
	v_pk_mul_f32 v[218:219], v[0:1], v[218:219] op_sel_hi:[0,1]
	v_pk_mul_f32 v[218:219], v[232:233], v[218:219]
	v_pk_mul_f32 v[216:217], v[230:231], v[216:217]
	global_store_dwordx4 v[20:21], v[216:219], off offset:2048
	v_lshlrev_b32_e32 v148, 16, v190
	v_and_b32_e32 v149, 0xffff0000, v190
	v_lshlrev_b32_e32 v150, 16, v191
	v_and_b32_e32 v151, 0xffff0000, v191
	v_pk_mul_f32 v[148:149], v[0:1], v[148:149] op_sel_hi:[0,1]
	v_pk_mul_f32 v[150:151], v[0:1], v[150:151] op_sel_hi:[0,1]
	v_pk_mul_f32 v[150:151], v[236:237], v[150:151]
	v_pk_mul_f32 v[148:149], v[234:235], v[148:149]
	global_store_dwordx4 v[20:21], v[148:151], off offset:3072
	s_andn2_b64 exec, exec, s[14:15]
	s_cbranch_execnz .LBB0_18

; #define LAS __attribute__((address_space(3)))
; #define S_STAGE(bufoff, gbase, voff) do { _Pragma("unroll") for (int _i = 0; _i < 2; ++_i) \
;     __builtin_amdgcn_global_load_lds((const unsigned*)((gbase) + (voff)[_i]), (LAS unsigned*)(lds + (bufoff) + ldsw + _i * 8192), 16, 0, 0); } while (0)
; #define S_LDA(dst, b, h) do { _Pragma("unroll") for (int m = 0; m < 4; ++m) _Pragma("unroll") for (int k = 0; k < 2; ++k) dst[m][k] = *(const LAS bf16x8*)(lds + S_SA(b, h) + aoff + m * 2048 + k * 1024); } while (0)
; #define S_LDB(dst, b, h) do { _Pragma("unroll") for (int n = 0; n < 2; ++n) _Pragma("unroll") for (int k = 0; k < 2; ++k) dst[n][k] = *(const LAS bf16x8*)(lds + S_SB(b, h) + boff + n * 2048 + k * 1024); } while (0)
; #define S_MMA(ai, bj, At_, Bt_) do { __builtin_amdgcn_s_setprio(1); _Pragma("unroll") for (int m = 0; m < 4; ++m) _Pragma("unroll") for (int n = 0; n < 2; ++n) _Pragma("unroll") for (int k = 0; k < 2; ++k) \
;     acc[ai][bj][m][n] = __builtin_amdgcn_mfma_f32_16x16x32_bf16(Bt_[n][k], At_[m][k], acc[ai][bj][m][n], 0, 0, 0); __builtin_amdgcn_s_setprio(0); } while (0)
; #define S_BAR __builtin_amdgcn_s_barrier()
; DI void gemm_phase(LAS unsigned char* lds, const GemmDesc& d, float* __restrict__ X) {
;     ...
;     int pm2 = 0, pn2 = 0; const bool has_next = tile_of(ui + 1, pm2, pn2);
;     const char* nA = has_next ? opA(pm2, pn2) : cA; const char* nB = has_next ? opB(pm2, pn2) : cB;
;     LAS float* rsl = (LAS float*)(lds + 131072 + (ui & 1) * 1024);
;     if (ui == 0 && d.epi != EPI_RESID) { if (ktid < 256) rsl[ktid] = row_rstd(d.P, d.np, d.inv_dim, pm * 256 + ktid); }
;     for (int t = 0; t < nt; t += 2) {
;       const bool last = (t == nt - 2);
;       const char* a1 = cA + (size_t)(t + 1) * kstepA;
;       const char* a2 = last ? nA : cA + (size_t)(t + 2) * kstepA; const char* b2 = last ? nB : cB + (size_t)(t + 2) * kstepB;
;       const char* a3 = a2 + kstepA; const char* b3 = b2 + kstepB;
;       S_LDB(B0, 0, 0); S_LDB(B1, 0, 1); S_SCHED; S_LDA(At, 0, 0); S_STAGE(S_SA(1, 1), a1 + hstepA, voffA);
;       S_WAIT_V(8); S_WAIT_L(0); S_BAR; S_MMA(0, 0, At, B0); S_MMA(0, 1, At, B1); S_BAR; S_SCHED;
;       S_LDA(At, 0, 1); S_STAGE(S_SB(0, 0), b2, voffB); S_STAGE(S_SB(0, 1), b2 + hstepB, voffB); S_STAGE(S_SA(0, 0), a2, voffA);
;       S_WAIT_V(8); S_WAIT_L(0); S_BAR; S_MMA(1, 0, At, B0); S_MMA(1, 1, At, B1); S_BAR; S_SCHED;
.LBB0_345:
	s_or_b64 exec, exec, s[78:79]
	s_add_u32 s20, s88, s27
	s_addc_u32 s21, s89, 0
	s_add_u32 s64, s90, 0x100
	s_addc_u32 s69, s91, 0
	s_mov_b64 s[90:91], 0
	s_waitcnt vmcnt(0)
	s_add_u32 s14, s90, 1
	s_addc_u32 s15, s91, 0
	s_add_u32 vcc_lo, s90, 2
	s_addc_u32 vcc_hi, s91, 0
	s_lshl_b64 s[78:79], vcc, s8
	s_add_u32 s56, s88, s78
	s_addc_u32 s57, s89, s79
	s_cmp_eq_u32 s9, s90
	s_cselect_b32 s78, s12, s56
	s_cselect_b32 s79, s13, s57
	s_cselect_b32 s56, s86, s64
	s_cselect_b32 s57, s87, s69
	s_add_u32 s90, s78, s0
	s_addc_u32 s91, s79, 0
	s_add_i32 s93, 0, 0x10000
	v_add_u32_e32 v0, s93, v174
	s_add_i32 s6, 0, 0x14000
	ds_read_b128 v[130:133], v0
	ds_read_b128 v[134:137], v0 offset:1024
	ds_read_b128 v[138:141], v0 offset:2048
	ds_read_b128 v[142:145], v0 offset:3072
	v_add_u32_e32 v0, s6, v174
	ds_read_b128 v[158:161], v0
	ds_read_b128 v[162:165], v0 offset:1024
	ds_read_b128 v[166:169], v0 offset:2048
	ds_read_b128 v[170:173], v0 offset:3072
	s_lshl_b64 s[14:15], s[14:15], s8
	s_add_u32 s14, s20, s14
	s_addc_u32 s15, s21, s15
	v_lshl_add_u64 v[192:193], s[14:15], 0, v[148:149]
	s_add_i32 m0, s55, 0xc000
	ds_read_b128 v[180:183], v147
	ds_read_b128 v[184:187], v147 offset:1024
	ds_read_b128 v[188:191], v147 offset:2048
	ds_read_b128 v[196:199], v147 offset:3072
	ds_read_b128 v[200:203], v147 offset:4096
	ds_read_b128 v[216:219], v147 offset:5120
	ds_read_b128 v[222:225], v147 offset:6144
	ds_read_b128 v[226:229], v147 offset:7168
	global_load_lds_dwordx4 v[192:193], off
	v_lshl_add_u64 v[192:193], s[14:15], 0, v[152:153]
	s_add_i32 m0, s55, 0xe000
	s_nop 0
	global_load_lds_dwordx4 v[192:193], off
	s_waitcnt vmcnt(8)
	s_waitcnt lgkmcnt(0)
	s_setprio 1
	s_barrier
	v_mfma_f32_16x16x32_bf16 v[126:129], v[130:133], v[180:183], 0
	v_mfma_f32_16x16x32_bf16 v[122:125], v[138:141], v[180:183], 0
	v_mfma_f32_16x16x32_bf16 v[110:113], v[130:133], v[188:191], 0
	v_mfma_f32_16x16x32_bf16 v[106:109], v[138:141], v[188:191], 0
	v_mfma_f32_16x16x32_bf16 v[94:97], v[130:133], v[200:203], 0
	v_mfma_f32_16x16x32_bf16 v[90:93], v[138:141], v[200:203], 0
	v_mfma_f32_16x16x32_bf16 v[78:81], v[130:133], v[222:225], 0
	v_mfma_f32_16x16x32_bf16 v[74:77], v[138:141], v[222:225], 0
	v_mfma_f32_16x16x32_bf16 v[126:129], v[134:137], v[184:187], v[126:129]
	v_mfma_f32_16x16x32_bf16 v[122:125], v[142:145], v[184:187], v[122:125]
	v_mfma_f32_16x16x32_bf16 v[110:113], v[134:137], v[196:199], v[110:113]
	v_mfma_f32_16x16x32_bf16 v[106:109], v[142:145], v[196:199], v[106:109]
	v_mfma_f32_16x16x32_bf16 v[94:97], v[134:137], v[216:219], v[94:97]
	v_mfma_f32_16x16x32_bf16 v[90:93], v[142:145], v[216:219], v[90:93]
	v_mfma_f32_16x16x32_bf16 v[78:81], v[134:137], v[226:229], v[78:81]
	v_mfma_f32_16x16x32_bf16 v[74:77], v[142:145], v[226:229], v[74:77]
	v_mfma_f32_16x16x32_bf16 v[118:121], v[158:161], v[180:183], 0
	v_mfma_f32_16x16x32_bf16 v[114:117], v[166:169], v[180:183], 0
	v_mfma_f32_16x16x32_bf16 v[102:105], v[158:161], v[188:191], 0
	v_mfma_f32_16x16x32_bf16 v[98:101], v[166:169], v[188:191], 0
	v_mfma_f32_16x16x32_bf16 v[86:89], v[158:161], v[200:203], 0
	v_mfma_f32_16x16x32_bf16 v[82:85], v[166:169], v[200:203], 0
	v_mfma_f32_16x16x32_bf16 v[70:73], v[158:161], v[222:225], 0
	v_mfma_f32_16x16x32_bf16 v[66:69], v[166:169], v[222:225], 0
	v_mfma_f32_16x16x32_bf16 v[118:121], v[162:165], v[184:187], v[118:121]
	v_mfma_f32_16x16x32_bf16 v[114:117], v[170:173], v[184:187], v[114:117]
	v_mfma_f32_16x16x32_bf16 v[102:105], v[162:165], v[196:199], v[102:105]
	v_mfma_f32_16x16x32_bf16 v[98:101], v[170:173], v[196:199], v[98:101]
	v_mfma_f32_16x16x32_bf16 v[86:89], v[162:165], v[216:219], v[86:89]
	v_mfma_f32_16x16x32_bf16 v[82:85], v[170:173], v[216:219], v[82:85]
	v_mfma_f32_16x16x32_bf16 v[70:73], v[162:165], v[226:229], v[70:73]
	v_mfma_f32_16x16x32_bf16 v[66:69], v[170:173], v[226:229], v[66:69]
	s_barrier
	s_setprio 0
	s_add_i32 s14, s93, s51
	v_lshl_add_u64 v[192:193], s[56:57], 0, v[150:151]
	s_mov_b32 m0, s14
	ds_read_b128 v[180:183], v147 offset:16384
	ds_read_b128 v[184:187], v147 offset:17408
	ds_read_b128 v[188:191], v147 offset:18432
	ds_read_b128 v[196:199], v147 offset:19456
	ds_read_b128 v[200:203], v147 offset:20480
	ds_read_b128 v[216:219], v147 offset:21504
	ds_read_b128 v[222:225], v147 offset:22528
	ds_read_b128 v[226:229], v147 offset:23552
	global_load_lds_dwordx4 v[192:193], off
	s_add_i32 m0, s14, 0x2000
	s_add_u32 s14, s56, s50
	v_lshl_add_u64 v[230:231], s[56:57], 0, v[154:155]
	s_addc_u32 s15, s57, 0
	s_add_i32 s6, s6, s51
	global_load_lds_dwordx4 v[230:231], off
	v_lshl_add_u64 v[232:233], s[14:15], 0, v[150:151]
	s_mov_b32 m0, s6
	v_lshl_add_u64 v[234:235], s[14:15], 0, v[154:155]
	global_load_lds_dwordx4 v[232:233], off
	s_add_i32 m0, s6, 0x2000
	v_lshl_add_u64 v[236:237], s[78:79], 0, v[148:149]
	global_load_lds_dwordx4 v[234:235], off
	s_mov_b32 m0, s55
	s_nop 0
	global_load_lds_dwordx4 v[236:237], off
	v_lshl_add_u64 v[236:237], s[78:79], 0, v[152:153]
	s_mov_b32 m0, s58
	s_nop 0
	global_load_lds_dwordx4 v[236:237], off
	s_waitcnt vmcnt(8)
	s_waitcnt lgkmcnt(0)
	s_setprio 1
	s_barrier
; #define S_STAGE(bufoff, gbase, voff) do { _Pragma("unroll") for (int _i = 0; _i < 2; ++_i) \
;     __builtin_amdgcn_global_load_lds((const unsigned*)((gbase) + (voff)[_i]), (LAS unsigned*)(lds + (bufoff) + ldsw + _i * 8192), 16, 0, 0); } while (0)
; #define S_LDA(dst, b, h) do { _Pragma("unroll") for (int m = 0; m < 4; ++m) _Pragma("unroll") for (int k = 0; k < 2; ++k) dst[m][k] = *(const LAS bf16x8*)(lds + S_SA(b, h) + aoff + m * 2048 + k * 1024); } while (0)
; #define S_LDB(dst, b, h) do { _Pragma("unroll") for (int n = 0; n < 2; ++n) _Pragma("unroll") for (int k = 0; k < 2; ++k) dst[n][k] = *(const LAS bf16x8*)(lds + S_SB(b, h) + boff + n * 2048 + k * 1024); } while (0)
; #define S_MMA(ai, bj, At_, Bt_) do { __builtin_amdgcn_s_setprio(1); _Pragma("unroll") for (int m = 0; m < 4; ++m) _Pragma("unroll") for (int n = 0; n < 2; ++n) _Pragma("unroll") for (int k = 0; k < 2; ++k) \
;     acc[ai][bj][m][n] = __builtin_amdgcn_mfma_f32_16x16x32_bf16(Bt_[n][k], At_[m][k], acc[ai][bj][m][n], 0, 0, 0); __builtin_amdgcn_s_setprio(0); } while (0)
; #define S_WAIT_V(n) asm volatile("s_waitcnt vmcnt(" #n ")" ::: "memory")
; #define S_WAIT_L(n) asm volatile("s_waitcnt lgkmcnt(" #n ")" ::: "memory")
; #define S_BAR __builtin_amdgcn_s_barrier()
; #define S_SCHED __builtin_amdgcn_sched_barrier(0)
; DI void gemm_phase(LAS unsigned char* lds, const GemmDesc& d, float* __restrict__ X) {
;     ...
;       S_WAIT_V(8); S_WAIT_L(0); S_BAR; S_MMA(1, 0, At, B0); S_MMA(1, 1, At, B1); S_BAR; S_SCHED;
;       S_LDB(B0, 1, 0); S_LDB(B1, 1, 1); S_SCHED; S_LDA(At, 1, 0); S_STAGE(S_SA(0, 1), a2 + hstepA, voffA);
;       S_WAIT_V(8); S_WAIT_L(0); S_BAR; S_MMA(0, 0, At, B0); S_MMA(0, 1, At, B1); S_BAR; S_SCHED;
;       S_LDA(At, 1, 1); S_STAGE(S_SB(1, 0), b3, voffB); S_STAGE(S_SB(1, 1), b3 + hstepB, voffB); S_STAGE(S_SA(1, 0), a3, voffA);
	v_mfma_f32_16x16x32_bf16 v[62:65], v[130:133], v[180:183], 0
	v_mfma_f32_16x16x32_bf16 v[58:61], v[138:141], v[180:183], 0
	v_mfma_f32_16x16x32_bf16 v[46:49], v[130:133], v[188:191], 0
	v_mfma_f32_16x16x32_bf16 v[42:45], v[138:141], v[188:191], 0
	v_mfma_f32_16x16x32_bf16 v[30:33], v[130:133], v[200:203], 0
	v_mfma_f32_16x16x32_bf16 v[26:29], v[138:141], v[200:203], 0
	v_mfma_f32_16x16x32_bf16 v[14:17], v[130:133], v[222:225], 0
	v_mfma_f32_16x16x32_bf16 v[10:13], v[138:141], v[222:225], 0
	v_mfma_f32_16x16x32_bf16 v[62:65], v[134:137], v[184:187], v[62:65]
	v_mfma_f32_16x16x32_bf16 v[58:61], v[142:145], v[184:187], v[58:61]
	v_mfma_f32_16x16x32_bf16 v[46:49], v[134:137], v[196:199], v[46:49]
	v_mfma_f32_16x16x32_bf16 v[42:45], v[142:145], v[196:199], v[42:45]
	v_mfma_f32_16x16x32_bf16 v[30:33], v[134:137], v[216:219], v[30:33]
	v_mfma_f32_16x16x32_bf16 v[26:29], v[142:145], v[216:219], v[26:29]
	v_mfma_f32_16x16x32_bf16 v[14:17], v[134:137], v[226:229], v[14:17]
	v_mfma_f32_16x16x32_bf16 v[10:13], v[142:145], v[226:229], v[10:13]
	v_mfma_f32_16x16x32_bf16 v[54:57], v[158:161], v[180:183], 0
	v_mfma_f32_16x16x32_bf16 v[50:53], v[166:169], v[180:183], 0
	v_mfma_f32_16x16x32_bf16 v[38:41], v[158:161], v[188:191], 0
	v_mfma_f32_16x16x32_bf16 v[34:37], v[166:169], v[188:191], 0
	v_mfma_f32_16x16x32_bf16 v[22:25], v[158:161], v[200:203], 0
	v_mfma_f32_16x16x32_bf16 v[18:21], v[166:169], v[200:203], 0
	v_mfma_f32_16x16x32_bf16 v[6:9], v[158:161], v[222:225], 0
	v_mfma_f32_16x16x32_bf16 v[2:5], v[166:169], v[222:225], 0
	v_mfma_f32_16x16x32_bf16 v[54:57], v[162:165], v[184:187], v[54:57]
	v_mfma_f32_16x16x32_bf16 v[50:53], v[170:173], v[184:187], v[50:53]
	v_mfma_f32_16x16x32_bf16 v[38:41], v[162:165], v[196:199], v[38:41]
	v_mfma_f32_16x16x32_bf16 v[34:37], v[170:173], v[196:199], v[34:37]
	v_mfma_f32_16x16x32_bf16 v[22:25], v[162:165], v[216:219], v[22:25]
	v_mfma_f32_16x16x32_bf16 v[18:21], v[170:173], v[216:219], v[18:21]
	v_mfma_f32_16x16x32_bf16 v[6:9], v[162:165], v[226:229], v[6:9]
	v_mfma_f32_16x16x32_bf16 v[2:5], v[170:173], v[226:229], v[2:5]
	s_barrier
	s_setprio 0
	s_add_i32 s6, 0, 0x18000
	v_add_u32_e32 v0, s6, v174
	s_add_i32 s56, 0, 0x1c000
	ds_read_b128 v[130:133], v0
	ds_read_b128 v[134:137], v0 offset:1024
	ds_read_b128 v[138:141], v0 offset:2048
	ds_read_b128 v[142:145], v0 offset:3072
	v_add_u32_e32 v0, s56, v174
	ds_read_b128 v[158:161], v0
	ds_read_b128 v[162:165], v0 offset:1024
	ds_read_b128 v[166:169], v0 offset:2048
	ds_read_b128 v[170:173], v0 offset:3072
	s_add_u32 s14, s78, s27
	s_addc_u32 s15, s79, 0
	s_mov_b32 m0, s59
	v_lshl_add_u64 v[236:237], s[14:15], 0, v[148:149]
	ds_read_b128 v[180:183], v147 offset:32768
	ds_read_b128 v[184:187], v147 offset:33792
	ds_read_b128 v[188:191], v147 offset:34816
	ds_read_b128 v[196:199], v147 offset:35840
	ds_read_b128 v[200:203], v147 offset:36864
	ds_read_b128 v[216:219], v147 offset:37888
	ds_read_b128 v[222:225], v147 offset:38912
	ds_read_b128 v[226:229], v147 offset:39936
	global_load_lds_dwordx4 v[236:237], off
	v_lshl_add_u64 v[236:237], s[14:15], 0, v[152:153]
	s_mov_b32 m0, s83
	s_nop 0
	global_load_lds_dwordx4 v[236:237], off
	s_waitcnt vmcnt(8)
	s_waitcnt lgkmcnt(0)
	s_setprio 1
	s_barrier
	v_mfma_f32_16x16x32_bf16 v[126:129], v[130:133], v[180:183], v[126:129]
	v_mfma_f32_16x16x32_bf16 v[122:125], v[138:141], v[180:183], v[122:125]
	v_mfma_f32_16x16x32_bf16 v[110:113], v[130:133], v[188:191], v[110:113]
	v_mfma_f32_16x16x32_bf16 v[106:109], v[138:141], v[188:191], v[106:109]
	v_mfma_f32_16x16x32_bf16 v[94:97], v[130:133], v[200:203], v[94:97]
	v_mfma_f32_16x16x32_bf16 v[90:93], v[138:141], v[200:203], v[90:93]
	v_mfma_f32_16x16x32_bf16 v[78:81], v[130:133], v[222:225], v[78:81]
	v_mfma_f32_16x16x32_bf16 v[74:77], v[138:141], v[222:225], v[74:77]
	v_mfma_f32_16x16x32_bf16 v[126:129], v[134:137], v[184:187], v[126:129]
	v_mfma_f32_16x16x32_bf16 v[122:125], v[142:145], v[184:187], v[122:125]
	v_mfma_f32_16x16x32_bf16 v[110:113], v[134:137], v[196:199], v[110:113]
	v_mfma_f32_16x16x32_bf16 v[106:109], v[142:145], v[196:199], v[106:109]
	v_mfma_f32_16x16x32_bf16 v[94:97], v[134:137], v[216:219], v[94:97]
	v_mfma_f32_16x16x32_bf16 v[90:93], v[142:145], v[216:219], v[90:93]
	v_mfma_f32_16x16x32_bf16 v[78:81], v[134:137], v[226:229], v[78:81]
	v_mfma_f32_16x16x32_bf16 v[74:77], v[142:145], v[226:229], v[74:77]
	v_mfma_f32_16x16x32_bf16 v[118:121], v[158:161], v[180:183], v[118:121]
	v_mfma_f32_16x16x32_bf16 v[114:117], v[166:169], v[180:183], v[114:117]
	v_mfma_f32_16x16x32_bf16 v[102:105], v[158:161], v[188:191], v[102:105]
	v_mfma_f32_16x16x32_bf16 v[98:101], v[166:169], v[188:191], v[98:101]
	v_mfma_f32_16x16x32_bf16 v[86:89], v[158:161], v[200:203], v[86:89]
	v_mfma_f32_16x16x32_bf16 v[82:85], v[166:169], v[200:203], v[82:85]
	v_mfma_f32_16x16x32_bf16 v[70:73], v[158:161], v[222:225], v[70:73]
	v_mfma_f32_16x16x32_bf16 v[66:69], v[166:169], v[222:225], v[66:69]
	v_mfma_f32_16x16x32_bf16 v[118:121], v[162:165], v[184:187], v[118:121]
	v_mfma_f32_16x16x32_bf16 v[114:117], v[170:173], v[184:187], v[114:117]
	v_mfma_f32_16x16x32_bf16 v[102:105], v[162:165], v[196:199], v[102:105]
	v_mfma_f32_16x16x32_bf16 v[98:101], v[170:173], v[196:199], v[98:101]
	v_mfma_f32_16x16x32_bf16 v[86:89], v[162:165], v[216:219], v[86:89]
	v_mfma_f32_16x16x32_bf16 v[82:85], v[170:173], v[216:219], v[82:85]
	v_mfma_f32_16x16x32_bf16 v[70:73], v[162:165], v[226:229], v[70:73]
	v_mfma_f32_16x16x32_bf16 v[66:69], v[170:173], v[226:229], v[66:69]
	s_barrier
; #define S_STAGE(bufoff, gbase, voff) do { _Pragma("unroll") for (int _i = 0; _i < 2; ++_i) \
;     __builtin_amdgcn_global_load_lds((const unsigned*)((gbase) + (voff)[_i]), (LAS unsigned*)(lds + (bufoff) + ldsw + _i * 8192), 16, 0, 0); } while (0)
; #define S_LDA(dst, b, h) do { _Pragma("unroll") for (int m = 0; m < 4; ++m) _Pragma("unroll") for (int k = 0; k < 2; ++k) dst[m][k] = *(const LAS bf16x8*)(lds + S_SA(b, h) + aoff + m * 2048 + k * 1024); } while (0)
; #define S_MMA(ai, bj, At_, Bt_) do { __builtin_amdgcn_s_setprio(1); _Pragma("unroll") for (int m = 0; m < 4; ++m) _Pragma("unroll") for (int n = 0; n < 2; ++n) _Pragma("unroll") for (int k = 0; k < 2; ++k) \
;     acc[ai][bj][m][n] = __builtin_amdgcn_mfma_f32_16x16x32_bf16(Bt_[n][k], At_[m][k], acc[ai][bj][m][n], 0, 0, 0); __builtin_amdgcn_s_setprio(0); } while (0)
; #define S_WAIT_V(n) asm volatile("s_waitcnt vmcnt(" #n ")" ::: "memory")
; #define S_WAIT_L(n) asm volatile("s_waitcnt lgkmcnt(" #n ")" ::: "memory")
; #define S_BAR __builtin_amdgcn_s_barrier()
; #define S_SCHED __builtin_amdgcn_sched_barrier(0)
; DI void gemm_phase(LAS unsigned char* lds, const GemmDesc& d, float* __restrict__ X) {
;     ...
;       S_LDA(At, 1, 1); S_STAGE(S_SB(1, 0), b3, voffB); S_STAGE(S_SB(1, 1), b3 + hstepB, voffB); S_STAGE(S_SA(1, 0), a3, voffA);
;       S_WAIT_V(8); S_WAIT_L(0); S_BAR; S_MMA(1, 0, At, B0); S_MMA(1, 1, At, B1); S_BAR; S_SCHED;
	s_setprio 0
	s_add_i32 s6, s6, s51
	v_lshl_add_u64 v[192:193], v[192:193], 0, s[98:99]
	s_mov_b32 m0, s6
	ds_read_b128 v[180:183], v147 offset:49152
	ds_read_b128 v[184:187], v147 offset:50176
	ds_read_b128 v[188:191], v147 offset:51200
	ds_read_b128 v[196:199], v147 offset:52224
	ds_read_b128 v[200:203], v147 offset:53248
	ds_read_b128 v[216:219], v147 offset:54272
	ds_read_b128 v[222:225], v147 offset:55296
	ds_read_b128 v[226:229], v147 offset:56320
	global_load_lds_dwordx4 v[192:193], off
	v_lshl_add_u64 v[192:193], v[230:231], 0, s[98:99]
	s_add_i32 m0, s6, 0x2000
	s_add_i32 s6, s56, s51
	global_load_lds_dwordx4 v[192:193], off
	v_lshl_add_u64 v[192:193], v[232:233], 0, s[98:99]
	s_mov_b32 m0, s6
	s_nop 0
	global_load_lds_dwordx4 v[192:193], off
	v_lshl_add_u64 v[192:193], v[234:235], 0, s[98:99]
	s_add_i32 m0, s6, 0x2000
	s_nop 0
	global_load_lds_dwordx4 v[192:193], off
	v_lshl_add_u64 v[192:193], s[90:91], 0, v[148:149]
	s_mov_b32 m0, s82
	s_nop 0
	global_load_lds_dwordx4 v[192:193], off
	v_lshl_add_u64 v[192:193], s[90:91], 0, v[152:153]
	s_mov_b32 m0, s94
	s_nop 0
	global_load_lds_dwordx4 v[192:193], off
	s_waitcnt vmcnt(8)
	s_waitcnt lgkmcnt(0)
	s_setprio 1
	s_barrier
	v_mfma_f32_16x16x32_bf16 v[62:65], v[130:133], v[180:183], v[62:65]
	v_mfma_f32_16x16x32_bf16 v[58:61], v[138:141], v[180:183], v[58:61]
	v_mfma_f32_16x16x32_bf16 v[46:49], v[130:133], v[188:191], v[46:49]
	v_mfma_f32_16x16x32_bf16 v[42:45], v[138:141], v[188:191], v[42:45]
	v_mfma_f32_16x16x32_bf16 v[30:33], v[130:133], v[200:203], v[30:33]
	v_mfma_f32_16x16x32_bf16 v[26:29], v[138:141], v[200:203], v[26:29]
	v_mfma_f32_16x16x32_bf16 v[14:17], v[130:133], v[222:225], v[14:17]
	v_mfma_f32_16x16x32_bf16 v[10:13], v[138:141], v[222:225], v[10:13]
	v_mfma_f32_16x16x32_bf16 v[62:65], v[134:137], v[184:187], v[62:65]
	v_mfma_f32_16x16x32_bf16 v[58:61], v[142:145], v[184:187], v[58:61]
	v_mfma_f32_16x16x32_bf16 v[46:49], v[134:137], v[196:199], v[46:49]
	v_mfma_f32_16x16x32_bf16 v[42:45], v[142:145], v[196:199], v[42:45]
	v_mfma_f32_16x16x32_bf16 v[30:33], v[134:137], v[216:219], v[30:33]
	v_mfma_f32_16x16x32_bf16 v[26:29], v[142:145], v[216:219], v[26:29]
	v_mfma_f32_16x16x32_bf16 v[14:17], v[134:137], v[226:229], v[14:17]
	v_mfma_f32_16x16x32_bf16 v[10:13], v[142:145], v[226:229], v[10:13]
	v_mfma_f32_16x16x32_bf16 v[54:57], v[158:161], v[180:183], v[54:57]
	v_mfma_f32_16x16x32_bf16 v[50:53], v[166:169], v[180:183], v[50:53]
	v_mfma_f32_16x16x32_bf16 v[38:41], v[158:161], v[188:191], v[38:41]
	v_mfma_f32_16x16x32_bf16 v[34:37], v[166:169], v[188:191], v[34:37]
	v_mfma_f32_16x16x32_bf16 v[22:25], v[158:161], v[200:203], v[22:25]
	v_mfma_f32_16x16x32_bf16 v[18:21], v[166:169], v[200:203], v[18:21]
	v_mfma_f32_16x16x32_bf16 v[6:9], v[158:161], v[222:225], v[6:9]
	v_mfma_f32_16x16x32_bf16 v[2:5], v[166:169], v[222:225], v[2:5]
	v_mfma_f32_16x16x32_bf16 v[54:57], v[162:165], v[184:187], v[54:57]
	v_mfma_f32_16x16x32_bf16 v[50:53], v[170:173], v[184:187], v[50:53]
	v_mfma_f32_16x16x32_bf16 v[38:41], v[162:165], v[196:199], v[38:41]
	v_mfma_f32_16x16x32_bf16 v[34:37], v[170:173], v[196:199], v[34:37]
	v_mfma_f32_16x16x32_bf16 v[22:25], v[162:165], v[216:219], v[22:25]
	v_mfma_f32_16x16x32_bf16 v[18:21], v[170:173], v[216:219], v[18:21]
	v_mfma_f32_16x16x32_bf16 v[6:9], v[162:165], v[226:229], v[6:9]
	v_mfma_f32_16x16x32_bf16 v[2:5], v[170:173], v[226:229], v[2:5]
	s_barrier
	s_setprio 0
	s_add_u32 s64, s64, 0x100
	s_addc_u32 s69, s69, 0
	s_cmp_ge_u32 vcc_lo, s1
	s_mov_b64 s[90:91], vcc
